# also the PP instance: accumulator clear removed, first of its two K-loop iterations peeled with C=0
# baseline (speedup 1.0000x reference)
; #define PG8_STAGE(bufoff, gbase, voff) do { _Pragma("unroll") for (int _i = 0; _i < 2; ++_i) \
;         __builtin_amdgcn_global_load_lds((const unsigned*)((const char*)(gbase) + (voff)[_i]), (LAS unsigned*)(lds + (bufoff) + ldsw + _i * 8192), 16, 0, 0); } while (0)
; #define PG8_LDA(dst, b, h) do { _Pragma("unroll") for (int m = 0; m < 4; ++m) _Pragma("unroll") for (int k = 0; k < 2; ++k) dst[m][k] = *(const LAS bf16x8*)(lds + PG8_SA(b, h) + aoff + m * 2048 + k * 1024); } while (0)
; #define PG8_LDB(dst, b, h) do { _Pragma("unroll") for (int n = 0; n < 2; ++n) _Pragma("unroll") for (int k = 0; k < 2; ++k) dst[n][k] = *(const LAS bf16x8*)(lds + PG8_SB(b, h) + boff + n * 2048 + k * 1024); } while (0)
; #define PG8_MMA(ai, bj, At, Bt) do { __builtin_amdgcn_s_setprio(1); _Pragma("unroll") for (int k = 0; k < 2; ++k) _Pragma("unroll") for (int m = 0; m < 4; ++m) _Pragma("unroll") for (int n = 0; n < 2; ++n) \
;         acc[ai][bj][m][n] = __builtin_amdgcn_mfma_f32_16x16x32_bf16(Bt[n][k], At[m][k], acc[ai][bj][m][n], 0, 0, 0); __builtin_amdgcn_s_setprio(0); } while (0)
; #define PG8_WAIT_V(n) asm volatile("s_waitcnt vmcnt(" #n ")" ::: "memory")
; template <class Epi, bool ALIGN_EPI>
; __device__ __forceinline__ void gemm_phase(LAS unsigned char* lds, const Gemm g, const StaticOrder& S, const Epi& E, const int tid) {
;     ...
;         const char* nA = has_next ? (const char*)g.A + (size_t)nxt.pm * tA + (size_t)nxt.pn * g.apn * 2 : cA; const char* nB = has_next ? (const char*)g.Bt + (size_t)nxt.pn * tB : cB;
;         for (int t = 0; t < nt; t += 2) {
;             const bool last = (t == nt - 2);
;             const char* a1 = cA + (size_t)(t + 1) * kstep;
;             const char* a2 = last ? nA : cA + (size_t)(t + 2) * kstep; const char* b2 = last ? nB : cB + (size_t)(t + 2) * kstep;
;             const char* a3 = a2 + kstep; const char* b3 = b2 + kstep;
;             PG8_LDB(B0, 0, 0); PG8_LDB(B1, 0, 1); PG8_SCHED; PG8_LDA(At, 0, 0); PG8_STAGE(PG8_SA(1, 1), a1 + hA, voffA);
;             PG8_WAIT_V(8); PG8_WAIT_L(0); PG8_BAR; PG8_MMA(0, 0, At, B0); PG8_MMA(0, 1, At, B1); PG8_BAR; PG8_SCHED;
;             PG8_LDA(At, 0, 1); PG8_STAGE(PG8_SB(0, 0), b2, voffB); PG8_STAGE(PG8_SB(0, 1), b2 + hB, voffB); PG8_STAGE(PG8_SA(0, 0), a2, voffA);
;             PG8_WAIT_V(8); PG8_WAIT_L(0); PG8_BAR; PG8_MMA(1, 0, At, B0); PG8_MMA(1, 1, At, B1); PG8_BAR; PG8_SCHED;
.LBB0_378:
	s_ashr_i32 s17, s16, 31
	s_lshl_b64 s[22:23], s[16:17], 17
	s_add_u32 s22, s4, s22
	s_addc_u32 s23, s5, s23
	s_and_b64 s[26:27], s[8:9], exec
	s_cselect_b32 s17, s23, s35
	s_cselect_b32 s59, s22, s34
	s_ashr_i32 s15, s14, 31
	s_lshl_b64 s[26:27], s[14:15], 17
	s_add_u32 s26, s7, s26
	s_addc_u32 s27, s25, s27
	s_and_b64 s[36:37], s[8:9], exec
	s_cselect_b32 s15, s27, s31
	s_cselect_b32 s60, s26, s30
	s_mov_b32 s40, 0
	s_mov_b64 s[36:37], -1
	s_mov_b64 s[38:39], 0
	s_add_u32 s41, s34, s40
	s_addc_u32 s46, s35, 0
	s_add_u32 s44, s41, 0x100
	s_addc_u32 s45, s46, 0
	s_and_b64 s[42:43], s[38:39], exec
	s_cselect_b32 s43, s17, s45
	s_cselect_b32 s42, s59, s44
	s_add_u32 s40, s30, s40
	s_addc_u32 s44, s31, 0
	s_add_u32 s40, s40, 0x100
	s_addc_u32 s44, s44, 0
	s_and_b64 s[38:39], s[38:39], exec
	s_cselect_b32 s45, s15, s44
	s_cselect_b32 s44, s60, s40
	s_add_i32 s39, 0, 0x14000
	s_add_u32 s48, s41, 0x10080
	s_addc_u32 s49, s46, 0
	s_add_i32 s68, s33, s50
	s_add_i32 m0, s51, 0xc000
	s_add_i32 s71, s51, 0xe000
	s_add_i32 s65, s68, 0x2000
	v_add_u32_e32 v138, s33, v141
	s_add_u32 s46, s44, 0x10000
	ds_read_b128 v[134:137], v138
	ds_read_b128 v[146:149], v138 offset:1024
	ds_read_b128 v[150:153], v138 offset:2048
	ds_read_b128 v[154:157], v138 offset:3072
	v_add_u32_e32 v138, s39, v141
	s_addc_u32 s47, s45, 0
	s_add_i32 s67, s39, s50
	ds_read_b128 v[158:161], v138
	ds_read_b128 v[162:165], v138 offset:1024
	ds_read_b128 v[174:177], v138 offset:2048
	ds_read_b128 v[178:181], v138 offset:3072
	s_add_i32 s66, s67, 0x2000
	s_add_i32 s64, 0, 0x18000
	s_add_i32 s63, 0, 0x1c000
	s_add_u32 s40, s42, 0x10000
	s_addc_u32 s41, s43, 0
	s_add_i32 s62, s64, s50
	s_add_i32 s61, s62, 0x2000
	s_add_u32 s38, s44, 0x10080
	s_addc_u32 s39, s45, 0
	s_add_i32 s70, s63, s50
	s_add_i32 s69, s70, 0x2000
	v_lshl_add_u64 v[138:139], s[48:49], 0, v[128:129]
	ds_read_b128 v[182:185], v145
	ds_read_b128 v[186:189], v145 offset:1024
	ds_read_b128 v[190:193], v145 offset:2048
	ds_read_b128 v[194:197], v145 offset:3072
	ds_read_b128 v[198:201], v145 offset:4096
	ds_read_b128 v[202:205], v145 offset:5120
	ds_read_b128 v[206:209], v145 offset:6144
	ds_read_b128 v[210:213], v145 offset:7168
	global_load_lds_dwordx4 v[138:139], off
	v_lshl_add_u64 v[138:139], s[48:49], 0, v[130:131]
	s_mov_b32 m0, s71
	s_nop 0
	global_load_lds_dwordx4 v[138:139], off
	s_waitcnt vmcnt(8)
	s_waitcnt lgkmcnt(0)
	s_barrier
	s_setprio 1
	s_waitcnt lgkmcnt(0)
	v_mfma_f32_16x16x32_bf16 v[124:127], v[134:137], v[182:185], 0
	v_mfma_f32_16x16x32_bf16 v[120:123], v[150:153], v[182:185], 0
	v_mfma_f32_16x16x32_bf16 v[108:111], v[134:137], v[190:193], 0
	v_mfma_f32_16x16x32_bf16 v[104:107], v[150:153], v[190:193], 0
	v_mfma_f32_16x16x32_bf16 v[92:95], v[134:137], v[198:201], 0
	v_mfma_f32_16x16x32_bf16 v[88:91], v[150:153], v[198:201], 0
	v_mfma_f32_16x16x32_bf16 v[76:79], v[134:137], v[206:209], 0
	v_mfma_f32_16x16x32_bf16 v[72:75], v[150:153], v[206:209], 0
	v_mfma_f32_16x16x32_bf16 v[124:127], v[146:149], v[186:189], v[124:127]
	v_mfma_f32_16x16x32_bf16 v[120:123], v[154:157], v[186:189], v[120:123]
	v_mfma_f32_16x16x32_bf16 v[108:111], v[146:149], v[194:197], v[108:111]
	v_mfma_f32_16x16x32_bf16 v[104:107], v[154:157], v[194:197], v[104:107]
	v_mfma_f32_16x16x32_bf16 v[92:95], v[146:149], v[202:205], v[92:95]
	v_mfma_f32_16x16x32_bf16 v[88:91], v[154:157], v[202:205], v[88:91]
	v_mfma_f32_16x16x32_bf16 v[76:79], v[146:149], v[210:213], v[76:79]
	v_mfma_f32_16x16x32_bf16 v[72:75], v[154:157], v[210:213], v[72:75]
	s_setprio 0
	s_setprio 1
	v_mfma_f32_16x16x32_bf16 v[116:119], v[158:161], v[182:185], 0
	v_mfma_f32_16x16x32_bf16 v[112:115], v[174:177], v[182:185], 0
	v_mfma_f32_16x16x32_bf16 v[100:103], v[158:161], v[190:193], 0
	v_mfma_f32_16x16x32_bf16 v[96:99], v[174:177], v[190:193], 0
	v_mfma_f32_16x16x32_bf16 v[84:87], v[158:161], v[198:201], 0
	v_mfma_f32_16x16x32_bf16 v[80:83], v[174:177], v[198:201], 0
	v_mfma_f32_16x16x32_bf16 v[68:71], v[158:161], v[206:209], 0
	v_mfma_f32_16x16x32_bf16 v[64:67], v[174:177], v[206:209], 0
	v_mfma_f32_16x16x32_bf16 v[116:119], v[162:165], v[186:189], v[116:119]
	v_mfma_f32_16x16x32_bf16 v[112:115], v[178:181], v[186:189], v[112:115]
	v_mfma_f32_16x16x32_bf16 v[100:103], v[162:165], v[194:197], v[100:103]
	v_mfma_f32_16x16x32_bf16 v[96:99], v[178:181], v[194:197], v[96:99]
	v_mfma_f32_16x16x32_bf16 v[84:87], v[162:165], v[202:205], v[84:87]
	v_mfma_f32_16x16x32_bf16 v[80:83], v[178:181], v[202:205], v[80:83]
	v_mfma_f32_16x16x32_bf16 v[68:71], v[162:165], v[210:213], v[68:71]
	v_mfma_f32_16x16x32_bf16 v[64:67], v[178:181], v[210:213], v[64:67]
	s_setprio 0
	s_barrier
	s_mov_b32 m0, s68
	v_lshl_add_u64 v[138:139], s[44:45], 0, v[168:169]
	ds_read_b128 v[182:185], v145 offset:16384
	ds_read_b128 v[186:189], v145 offset:17408
	ds_read_b128 v[190:193], v145 offset:18432
	ds_read_b128 v[194:197], v145 offset:19456
	ds_read_b128 v[198:201], v145 offset:20480
	ds_read_b128 v[202:205], v145 offset:21504
	ds_read_b128 v[206:209], v145 offset:22528
	ds_read_b128 v[210:213], v145 offset:23552
	global_load_lds_dwordx4 v[138:139], off
	v_lshl_add_u64 v[142:143], s[44:45], 0, v[132:133]
	s_mov_b32 m0, s65
	v_lshl_add_u64 v[166:167], s[46:47], 0, v[168:169]
	global_load_lds_dwordx4 v[142:143], off
	s_mov_b32 m0, s67
	v_lshl_add_u64 v[214:215], s[42:43], 0, v[130:131]
	global_load_lds_dwordx4 v[166:167], off
	v_lshl_add_u64 v[166:167], s[46:47], 0, v[132:133]
	s_mov_b32 m0, s66
	s_nop 0
	global_load_lds_dwordx4 v[166:167], off
	v_lshl_add_u64 v[166:167], s[42:43], 0, v[128:129]
	s_mov_b32 m0, s51
	s_nop 0
	global_load_lds_dwordx4 v[166:167], off
	s_mov_b32 m0, s52
	s_nop 0
	global_load_lds_dwordx4 v[214:215], off
	s_waitcnt vmcnt(8)
	s_waitcnt lgkmcnt(0)
	s_barrier
; #define PG8_STAGE(bufoff, gbase, voff) do { _Pragma("unroll") for (int _i = 0; _i < 2; ++_i) \
;         __builtin_amdgcn_global_load_lds((const unsigned*)((const char*)(gbase) + (voff)[_i]), (LAS unsigned*)(lds + (bufoff) + ldsw + _i * 8192), 16, 0, 0); } while (0)
; #define PG8_LDA(dst, b, h) do { _Pragma("unroll") for (int m = 0; m < 4; ++m) _Pragma("unroll") for (int k = 0; k < 2; ++k) dst[m][k] = *(const LAS bf16x8*)(lds + PG8_SA(b, h) + aoff + m * 2048 + k * 1024); } while (0)
; #define PG8_LDB(dst, b, h) do { _Pragma("unroll") for (int n = 0; n < 2; ++n) _Pragma("unroll") for (int k = 0; k < 2; ++k) dst[n][k] = *(const LAS bf16x8*)(lds + PG8_SB(b, h) + boff + n * 2048 + k * 1024); } while (0)
; #define PG8_MMA(ai, bj, At, Bt) do { __builtin_amdgcn_s_setprio(1); _Pragma("unroll") for (int k = 0; k < 2; ++k) _Pragma("unroll") for (int m = 0; m < 4; ++m) _Pragma("unroll") for (int n = 0; n < 2; ++n) \
;         acc[ai][bj][m][n] = __builtin_amdgcn_mfma_f32_16x16x32_bf16(Bt[n][k], At[m][k], acc[ai][bj][m][n], 0, 0, 0); __builtin_amdgcn_s_setprio(0); } while (0)
; #define PG8_WAIT_V(n) asm volatile("s_waitcnt vmcnt(" #n ")" ::: "memory")
; #define PG8_WAIT_L(n) asm volatile("s_waitcnt lgkmcnt(" #n ")" ::: "memory")
; #define PG8_BAR __builtin_amdgcn_s_barrier()
; #define PG8_SCHED __builtin_amdgcn_sched_barrier(0)
; template <class Epi, bool ALIGN_EPI>
; __device__ __forceinline__ void gemm_phase(LAS unsigned char* lds, const Gemm g, const StaticOrder& S, const Epi& E, const int tid) {
;     ...
;             PG8_WAIT_V(8); PG8_WAIT_L(0); PG8_BAR; PG8_MMA(1, 0, At, B0); PG8_MMA(1, 1, At, B1); PG8_BAR; PG8_SCHED;
;             PG8_LDB(B0, 1, 0); PG8_LDB(B1, 1, 1); PG8_SCHED; PG8_LDA(At, 1, 0); PG8_STAGE(PG8_SA(0, 1), a2 + hA, voffA);
;             PG8_WAIT_V(8); PG8_WAIT_L(0); PG8_BAR; PG8_MMA(0, 0, At, B0); PG8_MMA(0, 1, At, B1); PG8_BAR; PG8_SCHED;
	s_setprio 1
	s_waitcnt lgkmcnt(0)
	v_mfma_f32_16x16x32_bf16 v[60:63], v[134:137], v[182:185], 0
	v_mfma_f32_16x16x32_bf16 v[56:59], v[150:153], v[182:185], 0
	v_mfma_f32_16x16x32_bf16 v[48:51], v[134:137], v[190:193], 0
	v_mfma_f32_16x16x32_bf16 v[40:43], v[150:153], v[190:193], 0
	v_mfma_f32_16x16x32_bf16 v[32:35], v[134:137], v[198:201], 0
	v_mfma_f32_16x16x32_bf16 v[24:27], v[150:153], v[198:201], 0
	v_mfma_f32_16x16x32_bf16 v[16:19], v[134:137], v[206:209], 0
	v_mfma_f32_16x16x32_bf16 v[8:11], v[150:153], v[206:209], 0
	v_mfma_f32_16x16x32_bf16 v[60:63], v[146:149], v[186:189], v[60:63]
	v_mfma_f32_16x16x32_bf16 v[56:59], v[154:157], v[186:189], v[56:59]
	v_mfma_f32_16x16x32_bf16 v[48:51], v[146:149], v[194:197], v[48:51]
	v_mfma_f32_16x16x32_bf16 v[40:43], v[154:157], v[194:197], v[40:43]
	v_mfma_f32_16x16x32_bf16 v[32:35], v[146:149], v[202:205], v[32:35]
	v_mfma_f32_16x16x32_bf16 v[24:27], v[154:157], v[202:205], v[24:27]
	v_mfma_f32_16x16x32_bf16 v[16:19], v[146:149], v[210:213], v[16:19]
	v_mfma_f32_16x16x32_bf16 v[8:11], v[154:157], v[210:213], v[8:11]
	s_setprio 0
	s_setprio 1
	v_mfma_f32_16x16x32_bf16 v[52:55], v[158:161], v[182:185], 0
	v_mfma_f32_16x16x32_bf16 v[44:47], v[174:177], v[182:185], 0
	v_mfma_f32_16x16x32_bf16 v[36:39], v[158:161], v[190:193], 0
	v_mfma_f32_16x16x32_bf16 v[28:31], v[174:177], v[190:193], 0
	v_mfma_f32_16x16x32_bf16 v[20:23], v[158:161], v[198:201], 0
	v_mfma_f32_16x16x32_bf16 v[12:15], v[174:177], v[198:201], 0
	v_mfma_f32_16x16x32_bf16 v[4:7], v[158:161], v[206:209], 0
	v_mfma_f32_16x16x32_bf16 v[0:3], v[174:177], v[206:209], 0
	v_mfma_f32_16x16x32_bf16 v[52:55], v[162:165], v[186:189], v[52:55]
	v_mfma_f32_16x16x32_bf16 v[44:47], v[178:181], v[186:189], v[44:47]
	v_mfma_f32_16x16x32_bf16 v[36:39], v[162:165], v[194:197], v[36:39]
	v_mfma_f32_16x16x32_bf16 v[28:31], v[178:181], v[194:197], v[28:31]
	v_mfma_f32_16x16x32_bf16 v[20:23], v[162:165], v[202:205], v[20:23]
	v_mfma_f32_16x16x32_bf16 v[12:15], v[178:181], v[202:205], v[12:15]
	v_mfma_f32_16x16x32_bf16 v[4:7], v[162:165], v[210:213], v[4:7]
	v_mfma_f32_16x16x32_bf16 v[0:3], v[178:181], v[210:213], v[0:3]
	s_setprio 0
	s_barrier
	v_add_u32_e32 v140, s64, v141
	ds_read_b128 v[134:137], v140
	ds_read_b128 v[146:149], v140 offset:1024
	ds_read_b128 v[150:153], v140 offset:2048
	ds_read_b128 v[154:157], v140 offset:3072
	v_add_u32_e32 v140, s63, v141
	ds_read_b128 v[158:161], v140
	ds_read_b128 v[162:165], v140 offset:1024
	ds_read_b128 v[174:177], v140 offset:2048
	ds_read_b128 v[178:181], v140 offset:3072
	s_mov_b32 m0, s53
	v_lshl_add_u64 v[216:217], s[40:41], 0, v[128:129]
	ds_read_b128 v[182:185], v145 offset:32768
	ds_read_b128 v[186:189], v145 offset:33792
	ds_read_b128 v[190:193], v145 offset:34816
	ds_read_b128 v[194:197], v145 offset:35840
	ds_read_b128 v[198:201], v145 offset:36864
	ds_read_b128 v[202:205], v145 offset:37888
	ds_read_b128 v[206:209], v145 offset:38912
	ds_read_b128 v[210:213], v145 offset:39936
	global_load_lds_dwordx4 v[216:217], off
	v_lshl_add_u64 v[216:217], s[40:41], 0, v[130:131]
	s_mov_b32 m0, s54
	s_nop 0
	global_load_lds_dwordx4 v[216:217], off
	s_waitcnt vmcnt(8)
	s_waitcnt lgkmcnt(0)
	s_barrier
	s_setprio 1
	s_waitcnt lgkmcnt(0)
	v_mfma_f32_16x16x32_bf16 v[124:127], v[134:137], v[182:185], v[124:127]
	v_mfma_f32_16x16x32_bf16 v[120:123], v[150:153], v[182:185], v[120:123]
	v_mfma_f32_16x16x32_bf16 v[108:111], v[134:137], v[190:193], v[108:111]
	v_mfma_f32_16x16x32_bf16 v[104:107], v[150:153], v[190:193], v[104:107]
	v_mfma_f32_16x16x32_bf16 v[92:95], v[134:137], v[198:201], v[92:95]
	v_mfma_f32_16x16x32_bf16 v[88:91], v[150:153], v[198:201], v[88:91]
	v_mfma_f32_16x16x32_bf16 v[76:79], v[134:137], v[206:209], v[76:79]
	v_mfma_f32_16x16x32_bf16 v[72:75], v[150:153], v[206:209], v[72:75]
	v_mfma_f32_16x16x32_bf16 v[124:127], v[146:149], v[186:189], v[124:127]
	v_mfma_f32_16x16x32_bf16 v[120:123], v[154:157], v[186:189], v[120:123]
	v_mfma_f32_16x16x32_bf16 v[108:111], v[146:149], v[194:197], v[108:111]
	v_mfma_f32_16x16x32_bf16 v[104:107], v[154:157], v[194:197], v[104:107]
	v_mfma_f32_16x16x32_bf16 v[92:95], v[146:149], v[202:205], v[92:95]
	v_mfma_f32_16x16x32_bf16 v[88:91], v[154:157], v[202:205], v[88:91]
	v_mfma_f32_16x16x32_bf16 v[76:79], v[146:149], v[210:213], v[76:79]
	v_mfma_f32_16x16x32_bf16 v[72:75], v[154:157], v[210:213], v[72:75]
	s_setprio 0
	s_setprio 1
	v_mfma_f32_16x16x32_bf16 v[116:119], v[158:161], v[182:185], v[116:119]
	v_mfma_f32_16x16x32_bf16 v[112:115], v[174:177], v[182:185], v[112:115]
	v_mfma_f32_16x16x32_bf16 v[100:103], v[158:161], v[190:193], v[100:103]
	v_mfma_f32_16x16x32_bf16 v[96:99], v[174:177], v[190:193], v[96:99]
	v_mfma_f32_16x16x32_bf16 v[84:87], v[158:161], v[198:201], v[84:87]
	v_mfma_f32_16x16x32_bf16 v[80:83], v[174:177], v[198:201], v[80:83]
	v_mfma_f32_16x16x32_bf16 v[68:71], v[158:161], v[206:209], v[68:71]
	v_mfma_f32_16x16x32_bf16 v[64:67], v[174:177], v[206:209], v[64:67]
	v_mfma_f32_16x16x32_bf16 v[116:119], v[162:165], v[186:189], v[116:119]
	v_mfma_f32_16x16x32_bf16 v[112:115], v[178:181], v[186:189], v[112:115]
	v_mfma_f32_16x16x32_bf16 v[100:103], v[162:165], v[194:197], v[100:103]
	v_mfma_f32_16x16x32_bf16 v[96:99], v[178:181], v[194:197], v[96:99]
	v_mfma_f32_16x16x32_bf16 v[84:87], v[162:165], v[202:205], v[84:87]
	v_mfma_f32_16x16x32_bf16 v[80:83], v[178:181], v[202:205], v[80:83]
	v_mfma_f32_16x16x32_bf16 v[68:71], v[162:165], v[210:213], v[68:71]
	v_mfma_f32_16x16x32_bf16 v[64:67], v[178:181], v[210:213], v[64:67]
	s_setprio 0
	s_barrier
; #define PG8_STAGE(bufoff, gbase, voff) do { _Pragma("unroll") for (int _i = 0; _i < 2; ++_i) \
;         __builtin_amdgcn_global_load_lds((const unsigned*)((const char*)(gbase) + (voff)[_i]), (LAS unsigned*)(lds + (bufoff) + ldsw + _i * 8192), 16, 0, 0); } while (0)
; #define PG8_LDA(dst, b, h) do { _Pragma("unroll") for (int m = 0; m < 4; ++m) _Pragma("unroll") for (int k = 0; k < 2; ++k) dst[m][k] = *(const LAS bf16x8*)(lds + PG8_SA(b, h) + aoff + m * 2048 + k * 1024); } while (0)
; #define PG8_MMA(ai, bj, At, Bt) do { __builtin_amdgcn_s_setprio(1); _Pragma("unroll") for (int k = 0; k < 2; ++k) _Pragma("unroll") for (int m = 0; m < 4; ++m) _Pragma("unroll") for (int n = 0; n < 2; ++n) \
;         acc[ai][bj][m][n] = __builtin_amdgcn_mfma_f32_16x16x32_bf16(Bt[n][k], At[m][k], acc[ai][bj][m][n], 0, 0, 0); __builtin_amdgcn_s_setprio(0); } while (0)
; #define PG8_WAIT_V(n) asm volatile("s_waitcnt vmcnt(" #n ")" ::: "memory")
; #define PG8_WAIT_L(n) asm volatile("s_waitcnt lgkmcnt(" #n ")" ::: "memory")
; #define PG8_BAR __builtin_amdgcn_s_barrier()
; #define PG8_SCHED __builtin_amdgcn_sched_barrier(0)
; template <class Epi, bool ALIGN_EPI>
; __device__ __forceinline__ void gemm_phase(LAS unsigned char* lds, const Gemm g, const StaticOrder& S, const Epi& E, const int tid) {
;     ...
;         for (int t = 0; t < nt; t += 2) {
;             const bool last = (t == nt - 2);
;             const char* a1 = cA + (size_t)(t + 1) * kstep;
;             const char* a2 = last ? nA : cA + (size_t)(t + 2) * kstep; const char* b2 = last ? nB : cB + (size_t)(t + 2) * kstep;
;     ...
;             PG8_LDA(At, 1, 1); PG8_STAGE(PG8_SB(1, 0), b3, voffB); PG8_STAGE(PG8_SB(1, 1), b3 + hB, voffB); PG8_STAGE(PG8_SA(1, 0), a3, voffA);
;             PG8_WAIT_V(8); PG8_WAIT_L(0); PG8_BAR; PG8_MMA(1, 0, At, B0); PG8_MMA(1, 1, At, B1); PG8_BAR; PG8_SCHED;
	s_mov_b32 m0, s62
	v_lshl_add_u64 v[138:139], v[138:139], 0, s[92:93]
	ds_read_b128 v[182:185], v145 offset:49152
	ds_read_b128 v[186:189], v145 offset:50176
	ds_read_b128 v[190:193], v145 offset:51200
	ds_read_b128 v[194:197], v145 offset:52224
	ds_read_b128 v[198:201], v145 offset:53248
	ds_read_b128 v[202:205], v145 offset:54272
	ds_read_b128 v[206:209], v145 offset:55296
	ds_read_b128 v[210:213], v145 offset:56320
	global_load_lds_dwordx4 v[138:139], off
	v_lshl_add_u64 v[138:139], v[142:143], 0, s[92:93]
	s_mov_b32 m0, s61
	s_nop 0
	global_load_lds_dwordx4 v[138:139], off
	v_lshl_add_u64 v[138:139], s[38:39], 0, v[168:169]
	s_mov_b32 m0, s70
	s_nop 0
	global_load_lds_dwordx4 v[138:139], off
	v_lshl_add_u64 v[138:139], s[38:39], 0, v[132:133]
	s_mov_b32 m0, s69
	s_nop 0
	global_load_lds_dwordx4 v[138:139], off
	v_lshl_add_u64 v[138:139], v[166:167], 0, s[92:93]
	s_mov_b32 m0, s55
	s_nop 0
	global_load_lds_dwordx4 v[138:139], off
	v_lshl_add_u64 v[138:139], v[214:215], 0, s[92:93]
	s_mov_b32 m0, s56
	s_nop 0
	global_load_lds_dwordx4 v[138:139], off
	s_waitcnt vmcnt(8)
	s_waitcnt lgkmcnt(0)
	s_barrier
	s_setprio 1
	s_waitcnt lgkmcnt(0)
	v_mfma_f32_16x16x32_bf16 v[60:63], v[134:137], v[182:185], v[60:63]
	v_mfma_f32_16x16x32_bf16 v[56:59], v[150:153], v[182:185], v[56:59]
	v_mfma_f32_16x16x32_bf16 v[48:51], v[134:137], v[190:193], v[48:51]
	v_mfma_f32_16x16x32_bf16 v[40:43], v[150:153], v[190:193], v[40:43]
	v_mfma_f32_16x16x32_bf16 v[32:35], v[134:137], v[198:201], v[32:35]
	v_mfma_f32_16x16x32_bf16 v[24:27], v[150:153], v[198:201], v[24:27]
	v_mfma_f32_16x16x32_bf16 v[16:19], v[134:137], v[206:209], v[16:19]
	v_mfma_f32_16x16x32_bf16 v[8:11], v[150:153], v[206:209], v[8:11]
	v_mfma_f32_16x16x32_bf16 v[60:63], v[146:149], v[186:189], v[60:63]
	v_mfma_f32_16x16x32_bf16 v[56:59], v[154:157], v[186:189], v[56:59]
	v_mfma_f32_16x16x32_bf16 v[48:51], v[146:149], v[194:197], v[48:51]
	v_mfma_f32_16x16x32_bf16 v[40:43], v[154:157], v[194:197], v[40:43]
	v_mfma_f32_16x16x32_bf16 v[32:35], v[146:149], v[202:205], v[32:35]
	v_mfma_f32_16x16x32_bf16 v[24:27], v[154:157], v[202:205], v[24:27]
	v_mfma_f32_16x16x32_bf16 v[16:19], v[146:149], v[210:213], v[16:19]
	v_mfma_f32_16x16x32_bf16 v[8:11], v[154:157], v[210:213], v[8:11]
	s_setprio 0
	s_setprio 1
	v_mfma_f32_16x16x32_bf16 v[52:55], v[158:161], v[182:185], v[52:55]
	v_mfma_f32_16x16x32_bf16 v[44:47], v[174:177], v[182:185], v[44:47]
	v_mfma_f32_16x16x32_bf16 v[36:39], v[158:161], v[190:193], v[36:39]
	v_mfma_f32_16x16x32_bf16 v[28:31], v[174:177], v[190:193], v[28:31]
	v_mfma_f32_16x16x32_bf16 v[20:23], v[158:161], v[198:201], v[20:23]
	v_mfma_f32_16x16x32_bf16 v[12:15], v[174:177], v[198:201], v[12:15]
	v_mfma_f32_16x16x32_bf16 v[4:7], v[158:161], v[206:209], v[4:7]
	v_mfma_f32_16x16x32_bf16 v[0:3], v[174:177], v[206:209], v[0:3]
	v_mfma_f32_16x16x32_bf16 v[52:55], v[162:165], v[186:189], v[52:55]
	v_mfma_f32_16x16x32_bf16 v[44:47], v[178:181], v[186:189], v[44:47]
	v_mfma_f32_16x16x32_bf16 v[36:39], v[162:165], v[194:197], v[36:39]
	v_mfma_f32_16x16x32_bf16 v[28:31], v[178:181], v[194:197], v[28:31]
	v_mfma_f32_16x16x32_bf16 v[20:23], v[162:165], v[202:205], v[20:23]
	v_mfma_f32_16x16x32_bf16 v[12:15], v[178:181], v[202:205], v[12:15]
	v_mfma_f32_16x16x32_bf16 v[4:7], v[162:165], v[210:213], v[4:7]
	v_mfma_f32_16x16x32_bf16 v[0:3], v[178:181], v[210:213], v[0:3]
	s_setprio 0
	s_barrier
	s_movk_i32 s40, 0x100
	s_andn2_b64 vcc, exec, s[36:37]
	s_mov_b64 s[38:39], -1
	s_mov_b64 s[36:37], 0
